# v120 stack plus out-proj / ffn-down scheduler resume
# baseline (speedup 1.0000x reference)
.LBB0_115:
	s_mov_b32 s100, s53
	s_and_b64 s[20:21], s[54:55], exec
	s_cselect_b32 s20, s45, s57
	s_cselect_b32 s21, s44, s56
	s_cselect_b32 s62, s47, s59
	s_cselect_b32 s63, s46, s58
	s_add_u32 s56, s56, 0x40080
	s_addc_u32 s57, s57, 0
	s_add_u32 s64, s58, 0x100
	v_mov_b64_e32 v[0:1], 0
	s_addc_u32 s65, s59, 0
	s_mov_b32 s70, -2
	v_mov_b64_e32 v[2:3], 0
	v_mov_b64_e32 v[4:5], 0
	v_mov_b64_e32 v[6:7], 0
	v_mov_b64_e32 v[8:9], 0
	v_mov_b64_e32 v[10:11], 0
	v_mov_b64_e32 v[12:13], 0
	v_mov_b64_e32 v[14:15], 0
	v_mov_b64_e32 v[16:17], 0
	v_mov_b64_e32 v[18:19], 0
	v_mov_b64_e32 v[20:21], 0
	v_mov_b64_e32 v[22:23], 0
	v_mov_b64_e32 v[24:25], 0
	v_mov_b64_e32 v[26:27], 0
	v_mov_b64_e32 v[28:29], 0
	v_mov_b64_e32 v[30:31], 0
	v_mov_b64_e32 v[64:65], 0
	v_mov_b64_e32 v[66:67], 0
	v_mov_b64_e32 v[68:69], 0
	v_mov_b64_e32 v[70:71], 0
	v_mov_b64_e32 v[72:73], 0
	v_mov_b64_e32 v[74:75], 0
	v_mov_b64_e32 v[76:77], 0
	v_mov_b64_e32 v[78:79], 0
	v_mov_b64_e32 v[80:81], 0
	v_mov_b64_e32 v[82:83], 0
	v_mov_b64_e32 v[84:85], 0
	v_mov_b64_e32 v[86:87], 0
	v_mov_b64_e32 v[88:89], 0
	v_mov_b64_e32 v[90:91], 0
	v_mov_b64_e32 v[92:93], 0
	v_mov_b64_e32 v[94:95], 0
	v_mov_b64_e32 v[32:33], 0
	v_mov_b64_e32 v[34:35], 0
	v_mov_b64_e32 v[36:37], 0
	v_mov_b64_e32 v[38:39], 0
	v_mov_b64_e32 v[40:41], 0
	v_mov_b64_e32 v[42:43], 0
	v_mov_b64_e32 v[44:45], 0
	v_mov_b64_e32 v[46:47], 0
	v_mov_b64_e32 v[48:49], 0
	v_mov_b64_e32 v[50:51], 0
	v_mov_b64_e32 v[52:53], 0
	v_mov_b64_e32 v[54:55], 0
	v_mov_b64_e32 v[56:57], 0
	v_mov_b64_e32 v[58:59], 0
	v_mov_b64_e32 v[60:61], 0
	v_mov_b64_e32 v[62:63], 0
	v_mov_b64_e32 v[96:97], 0
	v_mov_b64_e32 v[98:99], 0
	v_mov_b64_e32 v[100:101], 0
	v_mov_b64_e32 v[102:103], 0
	v_mov_b64_e32 v[104:105], 0
	v_mov_b64_e32 v[106:107], 0
	v_mov_b64_e32 v[108:109], 0
	v_mov_b64_e32 v[110:111], 0
	v_mov_b64_e32 v[112:113], 0
	v_mov_b64_e32 v[114:115], 0
	v_mov_b64_e32 v[116:117], 0
	v_mov_b64_e32 v[118:119], 0
	v_mov_b64_e32 v[120:121], 0
	v_mov_b64_e32 v[122:123], 0
	v_mov_b64_e32 v[124:125], 0
	v_mov_b64_e32 v[126:127], 0

.LBB0_1250:
	s_mov_b32 s100, s60
	s_and_b64 s[20:21], s[52:53], exec
	s_cselect_b32 s20, s45, s55
	s_cselect_b32 s21, s44, s54
	s_cselect_b32 s70, s47, s57
	s_cselect_b32 vcc_lo, s46, s56
	s_add_u32 vcc_hi, s56, 0x100
	v_mov_b64_e32 v[0:1], 0
	s_addc_u32 s48, s57, 0
	s_mov_b32 s49, -2
	v_mov_b64_e32 v[2:3], 0
	v_mov_b64_e32 v[4:5], 0
	v_mov_b64_e32 v[6:7], 0
	v_mov_b64_e32 v[8:9], 0
	v_mov_b64_e32 v[10:11], 0
	v_mov_b64_e32 v[12:13], 0
	v_mov_b64_e32 v[14:15], 0
	v_mov_b64_e32 v[16:17], 0
	v_mov_b64_e32 v[18:19], 0
	v_mov_b64_e32 v[20:21], 0
	v_mov_b64_e32 v[22:23], 0
	v_mov_b64_e32 v[24:25], 0
	v_mov_b64_e32 v[26:27], 0
	v_mov_b64_e32 v[28:29], 0
	v_mov_b64_e32 v[30:31], 0
	v_mov_b64_e32 v[64:65], 0
	v_mov_b64_e32 v[66:67], 0
	v_mov_b64_e32 v[68:69], 0
	v_mov_b64_e32 v[70:71], 0
	v_mov_b64_e32 v[72:73], 0
	v_mov_b64_e32 v[74:75], 0
	v_mov_b64_e32 v[76:77], 0
	v_mov_b64_e32 v[78:79], 0
	v_mov_b64_e32 v[80:81], 0
	v_mov_b64_e32 v[82:83], 0
	v_mov_b64_e32 v[84:85], 0
	v_mov_b64_e32 v[86:87], 0
	v_mov_b64_e32 v[88:89], 0
	v_mov_b64_e32 v[90:91], 0
	v_mov_b64_e32 v[92:93], 0
	v_mov_b64_e32 v[94:95], 0
	v_mov_b64_e32 v[32:33], 0
	v_mov_b64_e32 v[34:35], 0
	v_mov_b64_e32 v[36:37], 0
	v_mov_b64_e32 v[38:39], 0
	v_mov_b64_e32 v[40:41], 0
	v_mov_b64_e32 v[42:43], 0
	v_mov_b64_e32 v[44:45], 0
	v_mov_b64_e32 v[46:47], 0
	v_mov_b64_e32 v[48:49], 0
	v_mov_b64_e32 v[50:51], 0
	v_mov_b64_e32 v[52:53], 0
	v_mov_b64_e32 v[54:55], 0
	v_mov_b64_e32 v[56:57], 0
	v_mov_b64_e32 v[58:59], 0
	v_mov_b64_e32 v[60:61], 0
	v_mov_b64_e32 v[62:63], 0
	v_mov_b64_e32 v[96:97], 0
	v_mov_b64_e32 v[98:99], 0
	v_mov_b64_e32 v[100:101], 0
	v_mov_b64_e32 v[102:103], 0
	v_mov_b64_e32 v[104:105], 0
	v_mov_b64_e32 v[106:107], 0
	v_mov_b64_e32 v[108:109], 0
	v_mov_b64_e32 v[110:111], 0
	v_mov_b64_e32 v[112:113], 0
	v_mov_b64_e32 v[114:115], 0
	v_mov_b64_e32 v[116:117], 0
	v_mov_b64_e32 v[118:119], 0
	v_mov_b64_e32 v[120:121], 0
	v_mov_b64_e32 v[122:123], 0
	v_mov_b64_e32 v[124:125], 0
	v_mov_b64_e32 v[126:127], 0
